# KVQ/Wo/up/down K-loop heads aligned to 64 bytes (s_nop padding) on top of the GEMM prologue version
# speedup vs baseline: 1.0027x; 1.0027x over previous
.LBB0_874:
	s_add_u32 s38, s38, 0x80080
	s_addc_u32 s39, s39, 0
	s_add_u32 s13, s24, 0x100
	v_mov_b32_e32 v2, 0
	s_addc_u32 s15, s25, 0
	s_mov_b32 s23, -2
	v_mov_b32_e32 v3, v2
	v_mov_b32_e32 v4, v2
	v_mov_b32_e32 v5, v2
	v_mov_b32_e32 v6, v2
	v_mov_b32_e32 v7, v2
	v_mov_b32_e32 v8, v2
	v_mov_b32_e32 v9, v2
	v_mov_b32_e32 v14, v2
	v_mov_b32_e32 v15, v2
	v_mov_b32_e32 v16, v2
	v_mov_b32_e32 v17, v2
	v_mov_b32_e32 v22, v2
	v_mov_b32_e32 v23, v2
	v_mov_b32_e32 v24, v2
	v_mov_b32_e32 v25, v2
	v_mov_b32_e32 v30, v2
	v_mov_b32_e32 v31, v2
	v_mov_b32_e32 v32, v2
	v_mov_b32_e32 v33, v2
	v_mov_b32_e32 v38, v2
	v_mov_b32_e32 v39, v2
	v_mov_b32_e32 v40, v2
	v_mov_b32_e32 v41, v2
	v_mov_b32_e32 v46, v2
	v_mov_b32_e32 v47, v2
	v_mov_b32_e32 v48, v2
	v_mov_b32_e32 v49, v2
	v_mov_b32_e32 v54, v2
	v_mov_b32_e32 v55, v2
	v_mov_b32_e32 v56, v2
	v_mov_b32_e32 v57, v2
	v_mov_b32_e32 v10, v2
	v_mov_b32_e32 v11, v2
	v_mov_b32_e32 v12, v2
	v_mov_b32_e32 v13, v2
	v_mov_b32_e32 v18, v2
	v_mov_b32_e32 v19, v2
	v_mov_b32_e32 v20, v2
	v_mov_b32_e32 v21, v2
	v_mov_b32_e32 v26, v2
	v_mov_b32_e32 v27, v2
	v_mov_b32_e32 v28, v2
	v_mov_b32_e32 v29, v2
	v_mov_b32_e32 v34, v2
	v_mov_b32_e32 v35, v2
	v_mov_b32_e32 v36, v2
	v_mov_b32_e32 v37, v2
	v_mov_b32_e32 v42, v2
	v_mov_b32_e32 v43, v2
	v_mov_b32_e32 v44, v2
	v_mov_b32_e32 v45, v2
	v_mov_b32_e32 v50, v2
	v_mov_b32_e32 v51, v2
	v_mov_b32_e32 v52, v2
	v_mov_b32_e32 v53, v2
	v_mov_b32_e32 v58, v2
	v_mov_b32_e32 v59, v2
	v_mov_b32_e32 v60, v2
	v_mov_b32_e32 v61, v2
	v_mov_b32_e32 v62, v2
	v_mov_b32_e32 v63, v2
	v_mov_b32_e32 v64, v2
	v_mov_b32_e32 v65, v2
	v_mov_b32_e32 v66, v2
	v_mov_b32_e32 v67, v2
	v_mov_b32_e32 v68, v2
	v_mov_b32_e32 v69, v2
	v_mov_b32_e32 v70, v2
	v_mov_b32_e32 v71, v2
	v_mov_b32_e32 v72, v2
	v_mov_b32_e32 v73, v2
	v_mov_b32_e32 v78, v2
	v_mov_b32_e32 v79, v2
	v_mov_b32_e32 v80, v2
	v_mov_b32_e32 v81, v2
	v_mov_b32_e32 v86, v2
	v_mov_b32_e32 v87, v2
	v_mov_b32_e32 v88, v2
	v_mov_b32_e32 v89, v2
	v_mov_b32_e32 v94, v2
	v_mov_b32_e32 v95, v2
	v_mov_b32_e32 v96, v2
	v_mov_b32_e32 v97, v2
	v_mov_b32_e32 v102, v2
	v_mov_b32_e32 v103, v2
	v_mov_b32_e32 v104, v2
	v_mov_b32_e32 v105, v2
	v_mov_b32_e32 v110, v2
	v_mov_b32_e32 v111, v2
	v_mov_b32_e32 v112, v2
	v_mov_b32_e32 v113, v2
	v_mov_b32_e32 v118, v2
	v_mov_b32_e32 v119, v2
	v_mov_b32_e32 v120, v2
	v_mov_b32_e32 v121, v2
	v_mov_b32_e32 v74, v2
	v_mov_b32_e32 v75, v2
	v_mov_b32_e32 v76, v2
	v_mov_b32_e32 v77, v2
	v_mov_b32_e32 v82, v2
	v_mov_b32_e32 v83, v2
	v_mov_b32_e32 v84, v2
	v_mov_b32_e32 v85, v2
	v_mov_b32_e32 v90, v2
	v_mov_b32_e32 v91, v2
	v_mov_b32_e32 v92, v2
	v_mov_b32_e32 v93, v2
	v_mov_b32_e32 v98, v2
	v_mov_b32_e32 v99, v2
	v_mov_b32_e32 v100, v2
	v_mov_b32_e32 v101, v2
	v_mov_b32_e32 v106, v2
	v_mov_b32_e32 v107, v2
	v_mov_b32_e32 v108, v2
	v_mov_b32_e32 v109, v2
	v_mov_b32_e32 v114, v2
	v_mov_b32_e32 v115, v2
	v_mov_b32_e32 v116, v2
	v_mov_b32_e32 v117, v2
	v_mov_b32_e32 v122, v2
	v_mov_b32_e32 v123, v2
	v_mov_b32_e32 v124, v2
	v_mov_b32_e32 v125, v2
	v_mov_b32_e32 v126, v2
	v_mov_b32_e32 v127, v2
	v_mov_b32_e32 v128, v2
	v_mov_b32_e32 v129, v2
	.p2alignl 6, 3212836864

.LBB0_1020:
	s_add_u32 s18, s18, 0x80080
	s_addc_u32 s19, s19, 0
	s_add_u32 s13, s20, 0x100
	v_mov_b32_e32 v2, 0
	s_addc_u32 s26, s21, 0
	s_mov_b32 s27, -2
	v_mov_b32_e32 v3, v2
	v_mov_b32_e32 v4, v2
	v_mov_b32_e32 v5, v2
	v_mov_b32_e32 v6, v2
	v_mov_b32_e32 v7, v2
	v_mov_b32_e32 v8, v2
	v_mov_b32_e32 v9, v2
	v_mov_b32_e32 v18, v2
	v_mov_b32_e32 v19, v2
	v_mov_b32_e32 v20, v2
	v_mov_b32_e32 v21, v2
	v_mov_b32_e32 v22, v2
	v_mov_b32_e32 v23, v2
	v_mov_b32_e32 v24, v2
	v_mov_b32_e32 v25, v2
	s_waitcnt vmcnt(0)
	v_mov_b32_e32 v34, v2
	v_mov_b32_e32 v35, v2
	v_mov_b32_e32 v36, v2
	v_mov_b32_e32 v37, v2
	v_mov_b32_e32 v38, v2
	v_mov_b32_e32 v39, v2
	v_mov_b32_e32 v40, v2
	v_mov_b32_e32 v41, v2
	v_mov_b32_e32 v50, v2
	v_mov_b32_e32 v51, v2
	v_mov_b32_e32 v52, v2
	v_mov_b32_e32 v53, v2
	v_mov_b32_e32 v54, v2
	v_mov_b32_e32 v55, v2
	v_mov_b32_e32 v56, v2
	v_mov_b32_e32 v57, v2
	v_mov_b32_e32 v10, v2
	v_mov_b32_e32 v11, v2
	v_mov_b32_e32 v12, v2
	v_mov_b32_e32 v13, v2
	v_mov_b32_e32 v14, v2
	v_mov_b32_e32 v15, v2
	v_mov_b32_e32 v16, v2
	v_mov_b32_e32 v17, v2
	v_mov_b32_e32 v26, v2
	v_mov_b32_e32 v27, v2
	v_mov_b32_e32 v28, v2
	v_mov_b32_e32 v29, v2
	v_mov_b32_e32 v30, v2
	v_mov_b32_e32 v31, v2
	v_mov_b32_e32 v32, v2
	v_mov_b32_e32 v33, v2
	v_mov_b32_e32 v42, v2
	v_mov_b32_e32 v43, v2
	v_mov_b32_e32 v44, v2
	v_mov_b32_e32 v45, v2
	v_mov_b32_e32 v46, v2
	v_mov_b32_e32 v47, v2
	v_mov_b32_e32 v48, v2
	v_mov_b32_e32 v49, v2
	v_mov_b32_e32 v58, v2
	v_mov_b32_e32 v59, v2
	v_mov_b32_e32 v60, v2
	v_mov_b32_e32 v61, v2
	v_mov_b32_e32 v62, v2
	v_mov_b32_e32 v63, v2
	v_mov_b32_e32 v64, v2
	v_mov_b32_e32 v65, v2
	v_mov_b32_e32 v66, v2
	v_mov_b32_e32 v67, v2
	v_mov_b32_e32 v68, v2
	v_mov_b32_e32 v69, v2
	v_mov_b32_e32 v70, v2
	v_mov_b32_e32 v71, v2
	v_mov_b32_e32 v72, v2
	v_mov_b32_e32 v73, v2
	v_mov_b32_e32 v82, v2
	v_mov_b32_e32 v83, v2
	v_mov_b32_e32 v84, v2
	v_mov_b32_e32 v85, v2
	v_mov_b32_e32 v86, v2
	v_mov_b32_e32 v87, v2
	v_mov_b32_e32 v88, v2
	v_mov_b32_e32 v89, v2
	v_mov_b32_e32 v98, v2
	v_mov_b32_e32 v99, v2
	v_mov_b32_e32 v100, v2
	v_mov_b32_e32 v101, v2
	v_mov_b32_e32 v102, v2
	v_mov_b32_e32 v103, v2
	v_mov_b32_e32 v104, v2
	v_mov_b32_e32 v105, v2
	v_mov_b32_e32 v114, v2
	v_mov_b32_e32 v115, v2
	v_mov_b32_e32 v116, v2
	v_mov_b32_e32 v117, v2
	v_mov_b32_e32 v118, v2
	v_mov_b32_e32 v119, v2
	v_mov_b32_e32 v120, v2
	v_mov_b32_e32 v121, v2
	v_mov_b32_e32 v74, v2
	v_mov_b32_e32 v75, v2
	v_mov_b32_e32 v76, v2
	v_mov_b32_e32 v77, v2
	v_mov_b32_e32 v78, v2
	v_mov_b32_e32 v79, v2
	v_mov_b32_e32 v80, v2
	v_mov_b32_e32 v81, v2
	v_mov_b32_e32 v90, v2
	v_mov_b32_e32 v91, v2
	v_mov_b32_e32 v92, v2
	v_mov_b32_e32 v93, v2
	v_mov_b32_e32 v94, v2
	v_mov_b32_e32 v95, v2
	v_mov_b32_e32 v96, v2
	v_mov_b32_e32 v97, v2
	v_mov_b32_e32 v106, v2
	v_mov_b32_e32 v107, v2
	v_mov_b32_e32 v108, v2
	v_mov_b32_e32 v109, v2
	v_mov_b32_e32 v110, v2
	v_mov_b32_e32 v111, v2
	v_mov_b32_e32 v112, v2
	v_mov_b32_e32 v113, v2
	v_mov_b32_e32 v122, v2
	v_mov_b32_e32 v123, v2
	v_mov_b32_e32 v124, v2
	v_mov_b32_e32 v125, v2
	v_mov_b32_e32 v126, v2
	v_mov_b32_e32 v127, v2
	v_mov_b32_e32 v128, v2
	v_mov_b32_e32 v129, v2
	.p2alignl 6, 3212836864

.LBB0_1150:
	s_add_u32 s18, s18, 0x80080
	s_addc_u32 s19, s19, 0
	s_add_u32 s13, s20, 0x100
	v_mov_b32_e32 v2, 0
	s_addc_u32 s50, s21, 0
	s_mov_b32 s51, -2
	v_mov_b32_e32 v3, v2
	v_mov_b32_e32 v4, v2
	v_mov_b32_e32 v5, v2
	v_mov_b32_e32 v6, v2
	v_mov_b32_e32 v7, v2
	v_mov_b32_e32 v8, v2
	v_mov_b32_e32 v9, v2
	v_mov_b32_e32 v18, v2
	v_mov_b32_e32 v19, v2
	v_mov_b32_e32 v20, v2
	v_mov_b32_e32 v21, v2
	v_mov_b32_e32 v22, v2
	v_mov_b32_e32 v23, v2
	v_mov_b32_e32 v24, v2
	v_mov_b32_e32 v25, v2
	v_mov_b32_e32 v34, v2
	v_mov_b32_e32 v35, v2
	v_mov_b32_e32 v36, v2
	v_mov_b32_e32 v37, v2
	v_mov_b32_e32 v38, v2
	v_mov_b32_e32 v39, v2
	v_mov_b32_e32 v40, v2
	v_mov_b32_e32 v41, v2
	v_mov_b32_e32 v50, v2
	v_mov_b32_e32 v51, v2
	v_mov_b32_e32 v52, v2
	v_mov_b32_e32 v53, v2
	v_mov_b32_e32 v54, v2
	v_mov_b32_e32 v55, v2
	v_mov_b32_e32 v56, v2
	v_mov_b32_e32 v57, v2
	v_mov_b32_e32 v10, v2
	v_mov_b32_e32 v11, v2
	v_mov_b32_e32 v12, v2
	v_mov_b32_e32 v13, v2
	v_mov_b32_e32 v14, v2
	v_mov_b32_e32 v15, v2
	v_mov_b32_e32 v16, v2
	v_mov_b32_e32 v17, v2
	v_mov_b32_e32 v26, v2
	v_mov_b32_e32 v27, v2
	v_mov_b32_e32 v28, v2
	v_mov_b32_e32 v29, v2
	v_mov_b32_e32 v30, v2
	v_mov_b32_e32 v31, v2
	v_mov_b32_e32 v32, v2
	v_mov_b32_e32 v33, v2
	v_mov_b32_e32 v42, v2
	v_mov_b32_e32 v43, v2
	v_mov_b32_e32 v44, v2
	v_mov_b32_e32 v45, v2
	v_mov_b32_e32 v46, v2
	v_mov_b32_e32 v47, v2
	v_mov_b32_e32 v48, v2
	v_mov_b32_e32 v49, v2
	v_mov_b32_e32 v58, v2
	v_mov_b32_e32 v59, v2
	v_mov_b32_e32 v60, v2
	v_mov_b32_e32 v61, v2
	v_mov_b32_e32 v62, v2
	v_mov_b32_e32 v63, v2
	v_mov_b32_e32 v64, v2
	v_mov_b32_e32 v65, v2
	v_mov_b32_e32 v66, v2
	v_mov_b32_e32 v67, v2
	v_mov_b32_e32 v68, v2
	v_mov_b32_e32 v69, v2
	v_mov_b32_e32 v70, v2
	v_mov_b32_e32 v71, v2
	v_mov_b32_e32 v72, v2
	v_mov_b32_e32 v73, v2
	v_mov_b32_e32 v82, v2
	v_mov_b32_e32 v83, v2
	v_mov_b32_e32 v84, v2
	v_mov_b32_e32 v85, v2
	v_mov_b32_e32 v86, v2
	v_mov_b32_e32 v87, v2
	v_mov_b32_e32 v88, v2
	v_mov_b32_e32 v89, v2
	v_mov_b32_e32 v98, v2
	v_mov_b32_e32 v99, v2
	v_mov_b32_e32 v100, v2
	v_mov_b32_e32 v101, v2
	v_mov_b32_e32 v102, v2
	v_mov_b32_e32 v103, v2
	v_mov_b32_e32 v104, v2
	v_mov_b32_e32 v105, v2
	v_mov_b32_e32 v114, v2
	v_mov_b32_e32 v115, v2
	v_mov_b32_e32 v116, v2
	v_mov_b32_e32 v117, v2
	v_mov_b32_e32 v118, v2
	v_mov_b32_e32 v119, v2
	v_mov_b32_e32 v120, v2
	v_mov_b32_e32 v121, v2
	v_mov_b32_e32 v74, v2
	v_mov_b32_e32 v75, v2
	v_mov_b32_e32 v76, v2
	v_mov_b32_e32 v77, v2
	v_mov_b32_e32 v78, v2
	v_mov_b32_e32 v79, v2
	v_mov_b32_e32 v80, v2
	v_mov_b32_e32 v81, v2
	v_mov_b32_e32 v90, v2
	v_mov_b32_e32 v91, v2
	v_mov_b32_e32 v92, v2
	v_mov_b32_e32 v93, v2
	v_mov_b32_e32 v94, v2
	v_mov_b32_e32 v95, v2
	v_mov_b32_e32 v96, v2
	v_mov_b32_e32 v97, v2
	v_mov_b32_e32 v106, v2
	v_mov_b32_e32 v107, v2
	v_mov_b32_e32 v108, v2
	v_mov_b32_e32 v109, v2
	v_mov_b32_e32 v110, v2
	v_mov_b32_e32 v111, v2
	v_mov_b32_e32 v112, v2
	v_mov_b32_e32 v113, v2
	v_mov_b32_e32 v122, v2
	v_mov_b32_e32 v123, v2
	v_mov_b32_e32 v124, v2
	v_mov_b32_e32 v125, v2
	v_mov_b32_e32 v126, v2
	v_mov_b32_e32 v127, v2
	v_mov_b32_e32 v128, v2
	v_mov_b32_e32 v129, v2
	.p2alignl 6, 3212836864

.LBB0_1219:
	s_add_u32 s18, s18, 0x200080
	s_addc_u32 s19, s19, 0
	s_add_u32 s11, s20, 0x100
	v_mov_b32_e32 v2, 0
	s_addc_u32 s60, s21, 0
	s_mov_b32 s61, -2
	v_mov_b32_e32 v3, v2
	v_mov_b32_e32 v4, v2
	v_mov_b32_e32 v5, v2
	v_mov_b32_e32 v6, v2
	v_mov_b32_e32 v7, v2
	v_mov_b32_e32 v8, v2
	v_mov_b32_e32 v9, v2
	v_mov_b32_e32 v18, v2
	v_mov_b32_e32 v19, v2
	v_mov_b32_e32 v20, v2
	v_mov_b32_e32 v21, v2
	v_mov_b32_e32 v22, v2
	v_mov_b32_e32 v23, v2
	v_mov_b32_e32 v24, v2
	v_mov_b32_e32 v25, v2
	v_mov_b32_e32 v34, v2
	v_mov_b32_e32 v35, v2
	v_mov_b32_e32 v36, v2
	v_mov_b32_e32 v37, v2
	v_mov_b32_e32 v38, v2
	v_mov_b32_e32 v39, v2
	v_mov_b32_e32 v40, v2
	v_mov_b32_e32 v41, v2
	v_mov_b32_e32 v50, v2
	v_mov_b32_e32 v51, v2
	v_mov_b32_e32 v52, v2
	v_mov_b32_e32 v53, v2
	v_mov_b32_e32 v54, v2
	v_mov_b32_e32 v55, v2
	v_mov_b32_e32 v56, v2
	v_mov_b32_e32 v57, v2
	v_mov_b32_e32 v10, v2
	v_mov_b32_e32 v11, v2
	v_mov_b32_e32 v12, v2
	v_mov_b32_e32 v13, v2
	v_mov_b32_e32 v14, v2
	v_mov_b32_e32 v15, v2
	v_mov_b32_e32 v16, v2
	v_mov_b32_e32 v17, v2
	v_mov_b32_e32 v26, v2
	v_mov_b32_e32 v27, v2
	v_mov_b32_e32 v28, v2
	v_mov_b32_e32 v29, v2
	v_mov_b32_e32 v30, v2
	v_mov_b32_e32 v31, v2
	v_mov_b32_e32 v32, v2
	v_mov_b32_e32 v33, v2
	v_mov_b32_e32 v42, v2
	v_mov_b32_e32 v43, v2
	v_mov_b32_e32 v44, v2
	v_mov_b32_e32 v45, v2
	v_mov_b32_e32 v46, v2
	v_mov_b32_e32 v47, v2
	v_mov_b32_e32 v48, v2
	v_mov_b32_e32 v49, v2
	v_mov_b32_e32 v58, v2
	v_mov_b32_e32 v59, v2
	v_mov_b32_e32 v60, v2
	v_mov_b32_e32 v61, v2
	v_mov_b32_e32 v62, v2
	v_mov_b32_e32 v63, v2
	v_mov_b32_e32 v64, v2
	v_mov_b32_e32 v65, v2
	v_mov_b32_e32 v66, v2
	v_mov_b32_e32 v67, v2
	v_mov_b32_e32 v68, v2
	v_mov_b32_e32 v69, v2
	v_mov_b32_e32 v70, v2
	v_mov_b32_e32 v71, v2
	v_mov_b32_e32 v72, v2
	v_mov_b32_e32 v73, v2
	v_mov_b32_e32 v82, v2
	v_mov_b32_e32 v83, v2
	v_mov_b32_e32 v84, v2
	v_mov_b32_e32 v85, v2
	v_mov_b32_e32 v86, v2
	v_mov_b32_e32 v87, v2
	v_mov_b32_e32 v88, v2
	v_mov_b32_e32 v89, v2
	v_mov_b32_e32 v98, v2
	v_mov_b32_e32 v99, v2
	v_mov_b32_e32 v100, v2
	v_mov_b32_e32 v101, v2
	v_mov_b32_e32 v102, v2
	v_mov_b32_e32 v103, v2
	v_mov_b32_e32 v104, v2
	v_mov_b32_e32 v105, v2
	v_mov_b32_e32 v114, v2
	v_mov_b32_e32 v115, v2
	v_mov_b32_e32 v116, v2
	v_mov_b32_e32 v117, v2
	v_mov_b32_e32 v118, v2
	v_mov_b32_e32 v119, v2
	v_mov_b32_e32 v120, v2
	v_mov_b32_e32 v121, v2
	v_mov_b32_e32 v74, v2
	v_mov_b32_e32 v75, v2
	v_mov_b32_e32 v76, v2
	v_mov_b32_e32 v77, v2
	v_mov_b32_e32 v78, v2
	v_mov_b32_e32 v79, v2
	v_mov_b32_e32 v80, v2
	v_mov_b32_e32 v81, v2
	v_mov_b32_e32 v90, v2
	v_mov_b32_e32 v91, v2
	v_mov_b32_e32 v92, v2
	v_mov_b32_e32 v93, v2
	v_mov_b32_e32 v94, v2
	v_mov_b32_e32 v95, v2
	v_mov_b32_e32 v96, v2
	v_mov_b32_e32 v97, v2
	v_mov_b32_e32 v106, v2
	v_mov_b32_e32 v107, v2
	v_mov_b32_e32 v108, v2
	v_mov_b32_e32 v109, v2
	v_mov_b32_e32 v110, v2
	v_mov_b32_e32 v111, v2
	v_mov_b32_e32 v112, v2
	v_mov_b32_e32 v113, v2
	v_mov_b32_e32 v122, v2
	v_mov_b32_e32 v123, v2
	v_mov_b32_e32 v124, v2
	v_mov_b32_e32 v125, v2
	v_mov_b32_e32 v126, v2
	v_mov_b32_e32 v127, v2
	v_mov_b32_e32 v128, v2
	v_mov_b32_e32 v129, v2
	.p2alignl 6, 3212836864
